# MLA tile loop: exp2 of subtile 0 evaluated speculatively between chain 2's MFMAs into the consumed K1 fragment registers (scores intact; discarded when the running max is raised), V fragments read bet
# speedup vs baseline: 1.0071x; 1.0020x over previous
.LBB0_767:
	s_or_b64 exec, exec, s[0:1]
	global_load_dwordx4 v[132:135], v[186:187], off
	s_cmp_gt_u32 s48, s11
	s_cbranch_scc1 .LBB0_790
	s_bitcmp1_b32 s49, 0
	s_cselect_b32 s0, 0, 0x5800
	v_add_u32_e32 v16, s0, v211
	v_add_u32_e32 v16, v16, v144
	ds_read_b128 v[190:193], v16
	ds_read_b128 v[194:197], v16 offset:32
	ds_read_b128 v[222:225], v16 offset:64
	ds_read_b128 v[226:229], v16 offset:96
	ds_read_b128 v[230:233], v16 offset:128
	ds_read_b128 v[234:237], v16 offset:160
	s_cmp_lt_u32 s48, s11
	s_cselect_b64 s[30:31], -1, 0
	s_andn2_b64 s[80:81], exec, s[30:31]
	s_cmp_lt_u32 s48, s11
	s_cbranch_scc0 .Lmla_c1only
	s_waitcnt lgkmcnt(5)
	v_mfma_f32_32x32x16_bf16 v[84:99], v[190:193], v[124:127], v[18:33]
	s_waitcnt lgkmcnt(4)
	v_mfma_f32_32x32x16_bf16 v[84:99], v[194:197], v[120:123], v[84:99]
	ds_read_b128 v[238:241], v16 offset:6656
	ds_read_b128 v[242:245], v16 offset:6688
	ds_read_b128 v[248:251], v16 offset:6720
	ds_read_b128 v[252:255], v16 offset:6752
	ds_read_b128 v[2:5], v16 offset:6784
	ds_read_b128 v[6:9], v16 offset:6816
	s_waitcnt lgkmcnt(9)
	v_mfma_f32_32x32x16_bf16 v[84:99], v[222:225], v[116:119], v[84:99]
	s_waitcnt lgkmcnt(8)
	v_mfma_f32_32x32x16_bf16 v[84:99], v[226:229], v[112:115], v[84:99]
	s_waitcnt lgkmcnt(7)
	v_mfma_f32_32x32x16_bf16 v[84:99], v[230:233], v[108:111], v[84:99]
	s_waitcnt lgkmcnt(6)
	v_mfma_f32_32x32x16_bf16 v[84:99], v[234:237], v[104:107], v[84:99]
	s_waitcnt lgkmcnt(5)
	v_mfma_f32_32x32x16_bf16 v[34:49], v[238:241], v[124:127], v[18:33]
	v_add_u32_e32 v239, s0, v144
	v_add_u32_e32 v239, v239, v210
	ds_read_b128 v[190:193], v239 offset:13312
	ds_read_b128 v[194:197], v239 offset:13344
	ds_read_b128 v[222:225], v239 offset:17920
	ds_read_b128 v[226:229], v239 offset:17952
	ds_read_b128 v[10:13], v239 offset:13376
	ds_read_b128 v[230:233], v239 offset:13408
	ds_read_b128 v[100:103], v239 offset:17984
	ds_read_b128 v[234:237], v239 offset:18016
	s_waitcnt lgkmcnt(12)
	v_mfma_f32_32x32x16_bf16 v[34:49], v[242:245], v[120:123], v[34:49]
	v_exp_f32_e32 v238, v84
	v_exp_f32_e32 v239, v85
	v_exp_f32_e32 v240, v86
	v_exp_f32_e32 v241, v87
	s_waitcnt lgkmcnt(11)
	v_mfma_f32_32x32x16_bf16 v[34:49], v[248:251], v[116:119], v[34:49]
	v_exp_f32_e32 v242, v88
	v_exp_f32_e32 v243, v89
	v_exp_f32_e32 v244, v90
	v_exp_f32_e32 v245, v91
	s_waitcnt lgkmcnt(10)
	v_mfma_f32_32x32x16_bf16 v[34:49], v[252:255], v[112:115], v[34:49]
	v_exp_f32_e32 v248, v92
	v_exp_f32_e32 v249, v93
	v_exp_f32_e32 v250, v94
	v_exp_f32_e32 v251, v95
	s_waitcnt lgkmcnt(9)
	v_mfma_f32_32x32x16_bf16 v[34:49], v[2:5], v[108:111], v[34:49]
	v_exp_f32_e32 v252, v96
	v_exp_f32_e32 v253, v97
	v_exp_f32_e32 v254, v98
	v_exp_f32_e32 v255, v99
	s_waitcnt lgkmcnt(8)
	v_mfma_f32_32x32x16_bf16 v[34:49], v[6:9], v[104:107], v[34:49]
	v_max3_i32 v16, v84, v85, v86
	v_max3_i32 v16, v16, v87, v88
	v_max3_i32 v16, v16, v89, v90
	v_max3_i32 v16, v16, v91, v92
	v_max3_i32 v16, v16, v93, v94
	v_max3_i32 v16, v16, v95, v96
	v_max3_i32 v16, v16, v97, v98
	v_max_i32_e32 v16, v16, v99
	s_cmp_lg_u32 s25, s48
	s_cbranch_scc1 .Lmla_nomask1
	v_add_u32_e32 v2, v215, v216
	v_cmp_lt_i32_e32 vcc, -1, v2
	s_nop 1
	v_cndmask_b32_e32 v34, v218, v34, vcc
	v_cmp_lt_i32_e32 vcc, 0, v2
	s_nop 1
	v_cndmask_b32_e32 v35, v218, v35, vcc
	v_cmp_lt_i32_e32 vcc, 1, v2
	s_nop 1
	v_cndmask_b32_e32 v36, v218, v36, vcc
	v_cmp_lt_i32_e32 vcc, 2, v2
	s_nop 1
	v_cndmask_b32_e32 v37, v218, v37, vcc
	v_cmp_lt_i32_e32 vcc, 7, v2
	s_nop 1
	v_cndmask_b32_e32 v38, v218, v38, vcc
	v_cmp_lt_i32_e32 vcc, 8, v2
	s_nop 1
	v_cndmask_b32_e32 v39, v218, v39, vcc
	v_cmp_lt_i32_e32 vcc, 9, v2
	s_nop 1
	v_cndmask_b32_e32 v40, v218, v40, vcc
	v_cmp_lt_i32_e32 vcc, 10, v2
	s_nop 1
	v_cndmask_b32_e32 v41, v218, v41, vcc
	v_cmp_lt_i32_e32 vcc, 15, v2
	s_nop 1
	v_cndmask_b32_e32 v42, v218, v42, vcc
	v_cmp_lt_i32_e32 vcc, 16, v2
	s_nop 1
	v_cndmask_b32_e32 v43, v218, v43, vcc
	v_cmp_lt_i32_e32 vcc, 17, v2
	s_nop 1
	v_cndmask_b32_e32 v44, v218, v44, vcc
	v_cmp_lt_i32_e32 vcc, 18, v2
	s_nop 1
	v_cndmask_b32_e32 v45, v218, v45, vcc
	v_cmp_lt_i32_e32 vcc, 23, v2
	s_nop 1
	v_cndmask_b32_e32 v46, v218, v46, vcc
	v_cmp_lt_i32_e32 vcc, 24, v2
	s_nop 1
	v_cndmask_b32_e32 v47, v218, v47, vcc
	v_cmp_lt_i32_e32 vcc, 25, v2
	s_nop 1
	v_cndmask_b32_e32 v48, v218, v48, vcc
	v_cmp_lt_i32_e32 vcc, 26, v2
	s_nop 1
	v_cndmask_b32_e32 v49, v218, v49, vcc
.Lmla_nomask1:
	s_nop 1
	v_max3_i32 v3, v34, v35, v36
	v_max3_i32 v3, v3, v37, v38
	v_max3_i32 v3, v3, v39, v40
	v_max3_i32 v3, v3, v41, v42
	v_max3_i32 v3, v3, v43, v44
	v_max3_i32 v3, v3, v45, v46
	v_max3_i32 v3, v3, v47, v48
	v_max_i32_e32 v3, v3, v49
	v_max_i32_e32 v16, v16, v3
	v_cmp_lt_f32_e32 vcc, s47, v16
	s_cbranch_vccz .Lmla_specA
	s_branch .Lmla_raise

.Lmla_raise:
	v_max3_f32 v16, v84, s86, v85
	v_max3_f32 v16, v16, v86, v87
	v_max3_f32 v16, v16, v88, v89
	v_max3_f32 v16, v16, v90, v91
	v_max3_f32 v16, v16, v92, v93
	v_max3_f32 v16, v16, v94, v95
	v_max3_f32 v16, v16, v96, v97
	s_and_b64 vcc, exec, s[80:81]
	v_max3_f32 v16, v16, v98, v99
	s_cbranch_vccnz .LBB0_781
	v_max3_f32 v16, v16, v34, v35
	v_max3_f32 v16, v16, v36, v37
	v_max3_f32 v16, v16, v38, v39
	v_max3_f32 v16, v16, v40, v41
	v_max3_f32 v16, v16, v42, v43
	v_max3_f32 v16, v16, v44, v45
	v_max3_f32 v16, v16, v46, v47
	v_max3_f32 v16, v16, v48, v49

.LBB0_785:
	v_exp_f32_e32 v84, v84
	v_exp_f32_e32 v85, v85
	v_exp_f32_e32 v86, v86
	v_exp_f32_e32 v87, v87
	v_exp_f32_e32 v88, v88
	v_exp_f32_e32 v89, v89
	v_exp_f32_e32 v90, v90
	v_exp_f32_e32 v91, v91
	v_exp_f32_e32 v92, v92
	v_exp_f32_e32 v93, v93
	v_cvt_pk_bf16_f32 v238, v84, v85
	v_cvt_pk_bf16_f32 v239, v86, v87
	v_exp_f32_e32 v94, v94
	v_exp_f32_e32 v95, v95
	v_cvt_pk_bf16_f32 v240, v88, v89
	v_cvt_pk_bf16_f32 v241, v90, v91
	v_exp_f32_e32 v96, v96
	v_exp_f32_e32 v97, v97
	v_pk_add_f32 v[4:5], v[84:85], 0 op_sel_hi:[1,0]
	s_waitcnt lgkmcnt(0)
	v_mfma_f32_32x32x16_bf16 v[68:83], v[190:193], v[238:241], v[68:83]
	v_exp_f32_e32 v98, v98
	v_exp_f32_e32 v99, v99
	v_pk_add_f32 v[4:5], v[86:87], v[4:5]
	v_mfma_f32_32x32x16_bf16 v[52:67], v[222:225], v[238:241], v[52:67]
	v_cvt_pk_bf16_f32 v248, v92, v93
	v_cvt_pk_bf16_f32 v249, v94, v95
	v_cvt_pk_bf16_f32 v250, v96, v97
	v_pk_add_f32 v[4:5], v[88:89], v[4:5]
	v_cvt_pk_bf16_f32 v251, v98, v99
	v_pk_add_f32 v[4:5], v[90:91], v[4:5]
	v_pk_add_f32 v[4:5], v[92:93], v[4:5]
	v_mfma_f32_32x32x16_bf16 v[68:83], v[194:197], v[248:251], v[68:83]
	v_pk_add_f32 v[4:5], v[94:95], v[4:5]
	v_mfma_f32_32x32x16_bf16 v[52:67], v[226:229], v[248:251], v[52:67]
	v_pk_add_f32 v[4:5], v[96:97], v[4:5]
	v_pk_add_f32 v[4:5], v[98:99], v[4:5]
	s_and_b64 vcc, exec, s[80:81]
	s_cbranch_vccnz .LBB0_789
	s_branch .Lmla_s1
.Lmla_specA:
	s_waitcnt lgkmcnt(0)
	v_pk_add_f32 v[4:5], v[238:239], 0 op_sel_hi:[1,0]
	v_cvt_pk_bf16_f32 v238, v238, v239
	v_pk_add_f32 v[4:5], v[240:241], v[4:5]
	v_cvt_pk_bf16_f32 v239, v240, v241
	v_pk_add_f32 v[4:5], v[242:243], v[4:5]
	v_cvt_pk_bf16_f32 v240, v242, v243
	v_pk_add_f32 v[4:5], v[244:245], v[4:5]
	v_cvt_pk_bf16_f32 v241, v244, v245
	v_pk_add_f32 v[4:5], v[248:249], v[4:5]
	v_cvt_pk_bf16_f32 v248, v248, v249
	v_mfma_f32_32x32x16_bf16 v[68:83], v[190:193], v[238:241], v[68:83]
	v_pk_add_f32 v[4:5], v[250:251], v[4:5]
	v_cvt_pk_bf16_f32 v249, v250, v251
	v_mfma_f32_32x32x16_bf16 v[52:67], v[222:225], v[238:241], v[52:67]
	v_pk_add_f32 v[4:5], v[252:253], v[4:5]
	v_cvt_pk_bf16_f32 v250, v252, v253
	v_pk_add_f32 v[4:5], v[254:255], v[4:5]
	v_cvt_pk_bf16_f32 v251, v254, v255
	v_exp_f32_e32 v34, v34
	v_exp_f32_e32 v35, v35
	v_mfma_f32_32x32x16_bf16 v[68:83], v[194:197], v[248:251], v[68:83]
	v_exp_f32_e32 v36, v36
	v_exp_f32_e32 v37, v37
	v_mfma_f32_32x32x16_bf16 v[52:67], v[226:229], v[248:251], v[52:67]
	s_branch .Lmla_s1b

.Lmla_s1b:
	v_exp_f32_e32 v38, v38
	v_exp_f32_e32 v39, v39
	v_exp_f32_e32 v40, v40
	v_exp_f32_e32 v41, v41
	v_cvt_pk_bf16_f32 v252, v34, v35
	v_cvt_pk_bf16_f32 v253, v36, v37
	v_exp_f32_e32 v42, v42
	v_exp_f32_e32 v43, v43
	v_cvt_pk_bf16_f32 v254, v38, v39
	v_cvt_pk_bf16_f32 v255, v40, v41
	v_exp_f32_e32 v44, v44
	v_exp_f32_e32 v45, v45
	v_pk_add_f32 v[4:5], v[34:35], v[4:5]
	v_mfma_f32_32x32x16_bf16 v[68:83], v[10:13], v[252:255], v[68:83]
	v_exp_f32_e32 v46, v46
	v_exp_f32_e32 v47, v47
	v_mfma_f32_32x32x16_bf16 v[52:67], v[100:103], v[252:255], v[52:67]
	v_exp_f32_e32 v48, v48
	v_exp_f32_e32 v49, v49
	v_pk_add_f32 v[4:5], v[36:37], v[4:5]
	v_cvt_pk_bf16_f32 v242, v42, v43
	v_cvt_pk_bf16_f32 v243, v44, v45
	v_cvt_pk_bf16_f32 v244, v46, v47
	v_pk_add_f32 v[4:5], v[38:39], v[4:5]
	v_cvt_pk_bf16_f32 v245, v48, v49
	v_pk_add_f32 v[4:5], v[40:41], v[4:5]
	v_pk_add_f32 v[4:5], v[42:43], v[4:5]
	v_mfma_f32_32x32x16_bf16 v[68:83], v[230:233], v[242:245], v[68:83]
	v_pk_add_f32 v[4:5], v[44:45], v[4:5]
	v_mfma_f32_32x32x16_bf16 v[52:67], v[234:237], v[242:245], v[52:67]
	v_pk_add_f32 v[4:5], v[46:47], v[4:5]
	v_pk_add_f32 v[4:5], v[48:49], v[4:5]
.LBB0_789:
	v_add_f32_e32 v16, v4, v5
	v_add_f32_e32 v183, v183, v16
